# LN1 input rows, combine gathers and the final f32 output use non-temporal accesses
# baseline (speedup 1.0000x reference)
; #define LAS __attribute__((address_space(3)))
; __device__ __forceinline__ int fresh_tid() { int t = threadIdx.x; asm volatile("" : "+v"(t)); return t; }
; __device__ void phase_combine(const Params& p, int l, float* outp) {
;     const int tid = fresh_tid(), lane = tid & 63, wv = tid >> 6;
;     bf16_t* XB = (bf16_t*)(p.ws + WS_XB); const bf16_t* YB = (const bf16_t*)(p.ws + WS_YB); const int* SLOTOF = (const int*)(p.ws + WS_SLOTOF);
;     const float* g = p.ln_ffn_g + l * DM; const float* b = p.ln_ffn_b + l * DM;
;     f32x4 gv[4], bv[4];
; #pragma unroll
;     for (int j = 0; j < 4; ++j) { gv[j] = *(const f32x4*)(g + lane * 4 + 256 * j); bv[j] = *(const f32x4*)(b + lane * 4 + 256 * j); }
;     const int rstride = gridDim.x * 8;
;     int nslot = 0; u32x2 nraw[4];
;     { const int row0 = blockIdx.x * 8 + wv;
;       if (row0 < SEQ) { nslot = SLOTOF[row0 * NE + (lane & 15)];
; #pragma unroll
;           for (int j = 0; j < 4; ++j) nraw[j] = *(const u32x2*)(XB + (size_t)row0 * DM + lane * 4 + 256 * j); } }
; __device__ __forceinline__ void run_phase(const Params& p, int ph, LAS unsigned char* lds) {
;     unsigned char* ws = p.ws;
;     if (ph == 0) { phase_convert(p, lds); return; }
;     const int l = (ph - 1) / PH_PER_LAYER, k = (ph - 1) % PH_PER_LAYER;
;     bf16_t* PROJ = (bf16_t*)(ws + WS_PROJ); bf16_t* YCAT = (bf16_t*)(ws + WS_YCAT);
;     switch (k) {
;     case 0: {
.LBB0_31:
.LBB0_32:
	s_cmp_lg_u32 s16, 0
	v_writelane_b32 v255, s16, 37
	s_cbranch_scc0 .LBB0_42
	s_add_i32 s4, s16, -1
	s_mul_hi_i32 s5, s4, 0x2e8ba2e9
	s_lshr_b32 s6, s5, 31
	s_ashr_i32 s5, s5, 1
	s_add_i32 s26, s5, s6
	s_mul_i32 s5, s26, 11
	s_sub_i32 s4, s4, s5
	v_writelane_b32 v255, s4, 38
	s_cmp_lt_i32 s4, 5
	s_mov_b64 s[4:5], -1
	s_cbranch_scc1 .LBB0_338
	v_readlane_b32 s4, v255, 38
	s_cmp_lt_i32 s4, 8
	s_mov_b64 s[4:5], -1
	s_cbranch_scc1 .LBB0_132
	v_readlane_b32 s4, v255, 38
	s_cmp_lt_i32 s4, 9
	s_mov_b64 s[4:5], -1
	s_cbranch_scc1 .LBB0_112
	v_readlane_b32 s4, v255, 38
	s_cmp_lt_i32 s4, 10
	s_mov_b64 s[4:5], -1
	s_cbranch_scc1 .LBB0_92
	v_readlane_b32 s4, v255, 38
	s_cmp_eq_u32 s4, 10
	s_cbranch_scc0 .LBB0_91
	s_lshl_b32 s4, s26, 10
	s_ashr_i32 s5, s4, 31
	s_waitcnt vmcnt(0)
	v_mov_b32_e32 v32, v213
	s_lshl_b64 s[4:5], s[4:5], 2
	s_add_u32 s6, s78, s4
	v_lshlrev_b32_e32 v0, 2, v32
	s_addc_u32 s7, s79, s5
	v_and_b32_e32 v33, 0xfc, v0
	s_add_u32 s4, s80, s4
	v_lshlrev_b32_e32 v40, 2, v33
	s_addc_u32 s5, s81, s5
	global_load_dwordx4 v[0:3], v40, s[6:7]
	global_load_dwordx4 v[4:7], v40, s[6:7] offset:1024
	global_load_dwordx4 v[8:11], v40, s[4:5]
	global_load_dwordx4 v[12:15], v40, s[4:5] offset:1024
	global_load_dwordx4 v[16:19], v40, s[6:7] offset:2048
	global_load_dwordx4 v[20:23], v40, s[6:7] offset:3072
	global_load_dwordx4 v[24:27], v40, s[4:5] offset:2048
	global_load_dwordx4 v[28:31], v40, s[4:5] offset:3072
	v_ashrrev_i32_e32 v34, 6, v32
	v_readlane_b32 s4, v252, 7
	v_mov_b32_e32 v81, 0
	v_and_b32_e32 v146, 15, v32
	v_add_u32_e32 v80, s4, v34
	s_movk_i32 s4, 0x4000
	v_cmp_gt_i32_e32 vcc, s4, v80
	v_lshlrev_b32_e32 v188, 1, v33
	s_and_saveexec_b64 s[4:5], vcc
	s_cbranch_execz .LBB0_40
	v_lshl_or_b32 v32, v80, 4, v146
	v_ashrrev_i32_e32 v81, 31, v80
	v_ashrrev_i32_e32 v33, 31, v32
	v_lshlrev_b64 v[34:35], 11, v[80:81]
	v_lshl_add_u64 v[32:33], v[32:33], 2, s[28:29]
	v_lshl_add_u64 v[34:35], s[66:67], 0, v[34:35]
	v_lshl_add_u64 v[42:43], v[34:35], 0, v[188:189]
	global_load_dword v81, v[32:33], off
	global_load_dwordx2 v[38:39], v[42:43], off nt
	global_load_dwordx2 v[36:37], v[42:43], off offset:512 nt
	global_load_dwordx2 v[34:35], v[42:43], off offset:1024 nt
	s_nop 0
	global_load_dwordx2 v[32:33], v[42:43], off offset:1536 nt

; __device__ __forceinline__ float bf_lo(unsigned w) { return __uint_as_float(w << 16); }
; __device__ __forceinline__ float bf_hi(unsigned w) { return __uint_as_float(w & 0xffff0000u); }
; __device__ void phase_combine(const Params& p, int l, float* outp) {
;     ...
;     for (int row = blockIdx.x * 8 + wv; row < SEQ; row += rstride) {
;         f32x4 v[4];
;         const int myslot = nslot;
; #pragma unroll
;         for (int j = 0; j < 4; ++j) { const u32x2 w = nraw[j]; v[j] = (f32x4){bf_lo(w.x), bf_hi(w.x), bf_lo(w.y), bf_hi(w.y)} * ALPHA; }
;         if (row + rstride < SEQ) { nslot = SLOTOF[(row + rstride) * NE + (lane & 15)];
; #pragma unroll
;             for (int j = 0; j < 4; ++j) nraw[j] = *(const u32x2*)(XB + (size_t)(row + rstride) * DM + lane * 4 + 256 * j); }
.LBB0_44:
	v_add_u32_e32 v78, s30, v80
	s_movk_i32 s4, 0x4000
	v_cmp_gt_i32_e32 vcc, s4, v78
	s_movk_i32 s4, 0x3fff
	v_cmp_lt_i32_e64 s[4:5], s4, v78
	s_and_saveexec_b64 s[6:7], vcc
	s_cbranch_execz .LBB0_46
	v_lshl_or_b32 v40, v78, 4, v146
	v_ashrrev_i32_e32 v41, 31, v40
	v_ashrrev_i32_e32 v79, 31, v78
	v_lshl_add_u64 v[40:41], v[40:41], 2, s[28:29]
	v_lshlrev_b64 v[42:43], 11, v[78:79]
	v_lshl_add_u64 v[42:43], v[64:65], 0, v[42:43]
	global_load_dword v79, v[40:41], off
	global_load_dwordx2 v[70:71], v[42:43], off nt
	global_load_dwordx2 v[72:73], v[42:43], off offset:512 nt
	global_load_dwordx2 v[74:75], v[42:43], off offset:1024 nt
	global_load_dwordx2 v[76:77], v[42:43], off offset:1536 nt

; __device__ void phase_combine(const Params& p, int l, float* outp) {
;     ...
;         unsigned long long em = __ballot(myslot >= 0) & 0xffffull;
;         while (em) {
;             int sl[4];
; #pragma unroll
;             for (int k = 0; k < 4; ++k) { sl[k] = -1; if (em) { const int e = __builtin_ctzll(em); em &= em - 1; sl[k] = __builtin_amdgcn_readlane(myslot, e); } }
;             u32x2 yw[4][4];
; #pragma unroll
;             for (int k = 0; k < 4; ++k) if (sl[k] >= 0) {
; #pragma unroll
;                 for (int j = 0; j < 4; ++j) yw[k][j] = *(const u32x2*)(YB + (size_t)sl[k] * DM + lane * 4 + 256 * j); }
.LBB0_55:
	s_lshl_b64 s[18:19], s[90:91], 11
	v_lshl_add_u64 v[106:107], v[66:67], 0, s[18:19]
	global_load_dwordx2 v[82:83], v[106:107], off nt
	global_load_dwordx2 v[90:91], v[106:107], off offset:512 nt
	global_load_dwordx2 v[98:99], v[106:107], off offset:1024 nt
	s_nop 0
	global_load_dwordx2 v[106:107], v[106:107], off offset:1536 nt
.LBB0_56:
	s_cmp_gt_i32 s16, -1
	s_cselect_b64 s[18:19], -1, 0
	s_cmp_lt_i32 s16, 0
	s_cbranch_scc1 .LBB0_58
	s_mov_b32 s17, s91
	s_lshl_b64 s[16:17], s[16:17], 11
	v_lshl_add_u64 v[108:109], v[66:67], 0, s[16:17]
	global_load_dwordx2 v[84:85], v[108:109], off nt
	global_load_dwordx2 v[92:93], v[108:109], off offset:512 nt
	global_load_dwordx2 v[100:101], v[108:109], off offset:1024 nt
	s_nop 0
	global_load_dwordx2 v[108:109], v[108:109], off offset:1536 nt
.LBB0_58:
	s_cmp_gt_i32 s14, -1
	s_cselect_b64 s[16:17], -1, 0
	s_cmp_lt_i32 s14, 0
	s_cbranch_scc1 .LBB0_60
	s_mov_b32 s15, s91
	s_lshl_b64 s[14:15], s[14:15], 11
	v_lshl_add_u64 v[110:111], v[66:67], 0, s[14:15]
	global_load_dwordx2 v[86:87], v[110:111], off nt
	global_load_dwordx2 v[94:95], v[110:111], off offset:512 nt
	global_load_dwordx2 v[102:103], v[110:111], off offset:1024 nt
	s_nop 0
	global_load_dwordx2 v[110:111], v[110:111], off offset:1536 nt
.LBB0_60:
	s_cmp_gt_i32 s22, -1
	s_cselect_b64 s[14:15], -1, 0
	s_cmp_lt_i32 s22, 0
	s_cbranch_scc1 .LBB0_62
	s_mov_b32 s23, s91
	s_lshl_b64 s[22:23], s[22:23], 11
	v_lshl_add_u64 v[112:113], v[66:67], 0, s[22:23]
	global_load_dwordx2 v[88:89], v[112:113], off nt
	global_load_dwordx2 v[96:97], v[112:113], off offset:512 nt
	global_load_dwordx2 v[104:105], v[112:113], off offset:1024 nt
	s_nop 0
	global_load_dwordx2 v[112:113], v[112:113], off offset:1536 nt

; __device__ __forceinline__ unsigned cvt_pk_bf16(float lo, float hi) { unsigned r; asm("v_cvt_pk_bf16_f32 %0, %1, %2" : "=v"(r) : "v"(lo), "v"(hi)); return r; }
; __device__ void phase_combine(const Params& p, int l, float* outp) {
;     ...
;         for (int j = 0; j < 4; ++j) { v[j] = v[j] * rstd * gv[j] + bv[j];
;             if (l == NL - 1) *(f32x4*)(outp + (size_t)row * DM + lane * 4 + 256 * j) = v[j];
;             else { u32x2 w; w.x = cvt_pk_bf16(v[j][0], v[j][1]); w.y = cvt_pk_bf16(v[j][2], v[j][3]); *(u32x2*)(XB + (size_t)row * DM + lane * 4 + 256 * j) = w; } }
.LBB0_76:
	v_lshlrev_b64 v[34:35], 12, v[80:81]
	s_andn2_b64 vcc, exec, s[6:7]
	v_lshl_add_u64 v[46:47], v[68:69], 0, v[34:35]
	s_cbranch_vccnz .LBB0_78
	global_store_dwordx4 v[46:47], v[42:45], off nt

; __device__ __forceinline__ unsigned cvt_pk_bf16(float lo, float hi) { unsigned r; asm("v_cvt_pk_bf16_f32 %0, %1, %2" : "=v"(r) : "v"(lo), "v"(hi)); return r; }
; __device__ void phase_combine(const Params& p, int l, float* outp) {
;     ...
;         for (int j = 0; j < 4; ++j) { v[j] = v[j] * rstd * gv[j] + bv[j];
;             if (l == NL - 1) *(f32x4*)(outp + (size_t)row * DM + lane * 4 + 256 * j) = v[j];
;             else { u32x2 w; w.x = cvt_pk_bf16(v[j][0], v[j][1]); w.y = cvt_pk_bf16(v[j][2], v[j][3]); *(u32x2*)(XB + (size_t)row * DM + lane * 4 + 256 * j) = w; } }
.LBB0_80:
	s_andn2_b64 vcc, exec, s[14:15]
	s_cbranch_vccnz .LBB0_82
	global_store_dwordx4 v[46:47], v[38:41], off offset:1024 nt

; __device__ __forceinline__ unsigned cvt_pk_bf16(float lo, float hi) { unsigned r; asm("v_cvt_pk_bf16_f32 %0, %1, %2" : "=v"(r) : "v"(lo), "v"(hi)); return r; }
; __device__ void phase_combine(const Params& p, int l, float* outp) {
;     ...
;         for (int j = 0; j < 4; ++j) { v[j] = v[j] * rstd * gv[j] + bv[j];
;             if (l == NL - 1) *(f32x4*)(outp + (size_t)row * DM + lane * 4 + 256 * j) = v[j];
;             else { u32x2 w; w.x = cvt_pk_bf16(v[j][0], v[j][1]); w.y = cvt_pk_bf16(v[j][2], v[j][3]); *(u32x2*)(XB + (size_t)row * DM + lane * 4 + 256 * j) = w; } }
.LBB0_84:
	s_andn2_b64 vcc, exec, s[14:15]
	s_cbranch_vccnz .LBB0_86
	global_store_dwordx4 v[46:47], v[34:37], off offset:2048 nt

; __device__ __forceinline__ unsigned cvt_pk_bf16(float lo, float hi) { unsigned r; asm("v_cvt_pk_bf16_f32 %0, %1, %2" : "=v"(r) : "v"(lo), "v"(hi)); return r; }
; __device__ void phase_combine(const Params& p, int l, float* outp) {
;     ...
;         for (int j = 0; j < 4; ++j) { v[j] = v[j] * rstd * gv[j] + bv[j];
;             if (l == NL - 1) *(f32x4*)(outp + (size_t)row * DM + lane * 4 + 256 * j) = v[j];
;             else { u32x2 w; w.x = cvt_pk_bf16(v[j][0], v[j][1]); w.y = cvt_pk_bf16(v[j][2], v[j][3]); *(u32x2*)(XB + (size_t)row * DM + lane * 4 + 256 * j) = w; } }
.LBB0_88:
	s_andn2_b64 vcc, exec, s[6:7]
	s_cbranch_vccnz .LBB0_43
	global_store_dwordx4 v[46:47], v[32:35], off offset:3072 nt
	s_branch .LBB0_43

; #define LAS __attribute__((address_space(3)))
; __device__ __forceinline__ int fresh_tid() { int t = threadIdx.x; asm volatile("" : "+v"(t)); return t; }
; __device__ void phase_ln1_router(const Params& p, int l, LAS unsigned char* lds) {
;     LAS float* rw_s = (LAS float*)lds;
;     const int tid = fresh_tid(), lane = tid & 63, wv = tid >> 6;
;     const float* rw = p.router_w + (size_t)l * DM * NE;
;     for (int i0 = 0; i0 < DM * NE; i0 += 8 * NTHREADS) { float rr[8];
; #pragma unroll
;         for (int q = 0; q < 8; ++q) rr[q] = rw[i0 + q * NTHREADS + tid];
; #pragma unroll
;         for (int q = 0; q < 8; ++q) { const int i = i0 + q * NTHREADS + tid, d = i >> 4, e = i & 15; rw_s[e * RWP + d] = rr[q]; } }
;     __syncthreads();
.LBB0_310:
	s_andn2_b64 vcc, exec, s[4:5]
	s_cbranch_vccnz .LBB0_319
	s_ashr_i32 s27, s26, 31
	v_readlane_b32 s8, v252, 40
	s_lshl_b64 s[4:5], s[26:27], 16
	v_readlane_b32 s18, v252, 50
	s_waitcnt vmcnt(0)
	v_mov_b32_e32 v38, v213
	v_readlane_b32 s19, v252, 51
	s_add_u32 s4, s18, s4
	s_addc_u32 s5, s19, s5
	v_and_b32_e32 v0, 15, v38
	s_movk_i32 s6, 0x1010
	v_ashrrev_i32_e32 v39, 31, v38
	v_mad_u32_u24 v14, v0, s6, 0
	v_lshl_add_u64 v[0:1], v[38:39], 2, s[4:5]
	v_lshrrev_b32_e32 v172, 6, v38
	v_and_b32_e32 v173, 63, v38
	v_and_b32_e32 v174, 15, v38
	v_bfe_u32 v175, v38, 4, 2
	v_lshlrev_b32_e32 v187, 13, v172
	v_lshl_add_u32 v187, v175, 8, v187
	v_lshl_add_u32 v187, v174, 2, v187
	s_add_u32 s6, s4, 0x1000
	s_addc_u32 s7, s5, 0
	global_load_dword v92, v187, s[4:5]
	global_load_dword v93, v187, s[4:5] offset:64
	global_load_dword v94, v187, s[4:5] offset:128
	global_load_dword v95, v187, s[4:5] offset:192
	global_load_dword v96, v187, s[4:5] offset:1024
	global_load_dword v97, v187, s[4:5] offset:1088
	global_load_dword v98, v187, s[4:5] offset:1152
	global_load_dword v99, v187, s[4:5] offset:1216
	global_load_dword v100, v187, s[4:5] offset:2048
	global_load_dword v101, v187, s[4:5] offset:2112
	global_load_dword v102, v187, s[4:5] offset:2176
	global_load_dword v103, v187, s[4:5] offset:2240
	global_load_dword v104, v187, s[4:5] offset:3072
	global_load_dword v105, v187, s[4:5] offset:3136
	global_load_dword v106, v187, s[4:5] offset:3200
	global_load_dword v107, v187, s[4:5] offset:3264
	global_load_dword v108, v187, s[6:7]
	global_load_dword v109, v187, s[6:7] offset:64
	global_load_dword v110, v187, s[6:7] offset:128
	global_load_dword v111, v187, s[6:7] offset:192
	global_load_dword v112, v187, s[6:7] offset:1024
	global_load_dword v113, v187, s[6:7] offset:1088
	global_load_dword v114, v187, s[6:7] offset:1152
	global_load_dword v115, v187, s[6:7] offset:1216
	global_load_dword v116, v187, s[6:7] offset:2048
	global_load_dword v117, v187, s[6:7] offset:2112
	global_load_dword v118, v187, s[6:7] offset:2176
	global_load_dword v119, v187, s[6:7] offset:2240
	global_load_dword v120, v187, s[6:7] offset:3072
	global_load_dword v121, v187, s[6:7] offset:3136
	global_load_dword v122, v187, s[6:7] offset:3200
	global_load_dword v123, v187, s[6:7] offset:3264
	v_readlane_b32 s9, v252, 41
	v_readlane_b32 s10, v252, 42
	v_readlane_b32 s11, v252, 43
	v_readlane_b32 s12, v252, 44
	v_readlane_b32 s13, v252, 45
	v_readlane_b32 s14, v252, 46
	v_readlane_b32 s15, v252, 47
	v_readlane_b32 s16, v252, 48
	v_readlane_b32 s17, v252, 49
	v_readlane_b32 s20, v252, 52
	v_readlane_b32 s21, v252, 53
	v_readlane_b32 s22, v252, 54
	v_readlane_b32 s23, v252, 55
	v_mul_u32_u24_e32 v176, 0x1010, v172
	v_lshl_add_u32 v180, v173, 4, v176
	v_mul_u32_u24_e32 v181, 0x1010, v174
	v_lshl_add_u32 v181, v172, 9, v181
	v_lshl_add_u32 v181, v175, 4, v181
	v_lshlrev_b32_e32 v182, 10, v172
	v_lshl_add_u32 v182, v173, 2, v182
	v_add_u32_e32 v182, 0x10100, v182
	v_bfe_u32 v177, v38, 4, 1
	v_lshl_add_u32 v177, v172, 1, v177
	v_and_b32_e32 v178, 3, v177
	v_lshrrev_b32_e32 v179, 2, v177
	v_lshl_add_u32 v179, v179, 4, v174
	v_lshlrev_b32_e32 v183, 2, v179
	v_lshl_add_u32 v183, v178, 8, v183
	v_add_u32_e32 v183, 0x10100, v183
	v_readlane_b32 s4, v252, 7
	v_and_b32_e32 v178, 7, v177
	v_lshrrev_b32_e32 v179, 3, v177
	v_lshl_add_u32 v178, v179, 11, v178
	s_nop 1
	v_add_u32_e32 v178, s4, v178
	v_lshlrev_b32_e32 v184, 2, v178
	v_lshl_add_u32 v184, v174, 16, v184
	v_add_u32_e32 v184, 0x33601000, v184
	v_mov_b32_e32 v185, 0
	v_lshl_add_u64 v[184:185], s[86:87], 0, v[184:185]
	v_ashrrev_i32_e32 v0, 6, v38
	v_add_u32_e32 v32, s4, v0
	s_movk_i32 s4, 0x4000
	v_cmp_gt_i32_e32 vcc, s4, v32
	s_waitcnt lgkmcnt(0)
	s_barrier
	s_and_saveexec_b64 s[24:25], vcc
	s_cbranch_execz .LBB0_318
; __device__ __forceinline__ float bf_lo(unsigned w) { return __uint_as_float(w << 16); }
; __device__ __forceinline__ float bf_hi(unsigned w) { return __uint_as_float(w & 0xffff0000u); }
; __device__ void phase_ln1_router(const Params& p, int l, LAS unsigned char* lds) {
;     ...
;     const bf16_t* XP = (const bf16_t*)(p.ws + WS_XA); bf16_t* XB = (bf16_t*)(p.ws + WS_XB); float* AFF = (float*)(p.ws + WS_AFF);
;     const float* g = p.ln_mix_g + l * DM; const float* b = p.ln_mix_b + l * DM;
;     f32x4 gv[4], bv[4];
; #pragma unroll
;     for (int j = 0; j < 4; ++j) { gv[j] = *(const f32x4*)(g + lane * 4 + 256 * j); bv[j] = *(const f32x4*)(b + lane * 4 + 256 * j); }
;     const int rstride = gridDim.x * 8;
;     u32x2 raw[4];
;     { const int row0 = blockIdx.x * 8 + wv;
;       if (row0 < SEQ) {
; #pragma unroll
;           for (int j = 0; j < 4; ++j) raw[j] = *(const u32x2*)(XP + (size_t)row0 * DM + lane * 4 + 256 * j); } }
;     for (int row = blockIdx.x * 8 + wv; row < SEQ; row += rstride) {
;         f32x4 v[4]; float s = 0.f;
; #pragma unroll
;         for (int j = 0; j < 4; ++j) { const u32x2 w = raw[j]; v[j] = (f32x4){bf_lo(w.x), bf_hi(w.x), bf_lo(w.y), bf_hi(w.y)}; s += (v[j][0] + v[j][1]) + (v[j][2] + v[j][3]); }
;         if (row + rstride < SEQ) {
; #pragma unroll
;             for (int j = 0; j < 4; ++j) raw[j] = *(const u32x2*)(XP + (size_t)(row + rstride) * DM + lane * 4 + 256 * j); }
	s_lshl_b32 s4, s26, 10
	s_ashr_i32 s5, s4, 31
	v_readlane_b32 s8, v252, 40
	s_lshl_b64 s[4:5], s[4:5], 2
	v_readlane_b32 s16, v252, 48
	v_readlane_b32 s17, v252, 49
	s_add_u32 s6, s16, s4
	v_readlane_b32 s14, v252, 46
	s_addc_u32 s7, s17, s5
	v_readlane_b32 s15, v252, 47
	v_and_b32_e32 v39, 63, v38
	s_add_u32 s4, s14, s4
	v_lshlrev_b32_e32 v40, 4, v39
	s_addc_u32 s5, s15, s5
	global_load_dwordx4 v[0:3], v40, s[6:7] offset:3072
	global_load_dwordx4 v[4:7], v40, s[4:5] offset:3072
	global_load_dwordx4 v[8:11], v40, s[6:7] offset:2048
	global_load_dwordx4 v[12:15], v40, s[4:5] offset:2048
	global_load_dwordx4 v[16:19], v40, s[6:7] offset:1024
	global_load_dwordx4 v[20:23], v40, s[4:5] offset:1024
	global_load_dwordx4 v[24:27], v40, s[6:7]
	global_load_dwordx4 v[28:31], v40, s[4:5]
	v_ashrrev_i32_e32 v33, 31, v32
	v_readlane_b32 s4, v252, 59
	v_lshlrev_b64 v[34:35], 11, v[32:33]
	v_readlane_b32 s5, v252, 60
	v_lshlrev_b32_e32 v188, 3, v39
	v_and_b32_e32 v39, 64, v211
	v_lshl_add_u64 v[36:37], s[4:5], 0, v[34:35]
	v_lshl_add_u64 v[36:37], v[36:37], 0, v[188:189]
	global_load_dwordx2 v[54:55], v[36:37], off
	global_load_dwordx2 v[52:53], v[36:37], off offset:512
	global_load_dwordx2 v[50:51], v[36:37], off offset:1024
	global_load_dwordx2 v[48:49], v[36:37], off offset:1536
	v_add_u32_e32 v39, 64, v39
	v_xor_b32_e32 v41, 32, v211
	v_cmp_lt_i32_e32 vcc, v41, v39
	v_lshl_add_u64 v[36:37], s[4:5], 0, v[188:189]
	v_readlane_b32 s9, v252, 41
	v_cndmask_b32_e32 v41, v211, v41, vcc
	v_lshlrev_b32_e32 v64, 2, v41
	v_xor_b32_e32 v41, 16, v211
	v_cmp_lt_i32_e32 vcc, v41, v39
	v_readlane_b32 s10, v252, 42
	v_readlane_b32 s11, v252, 43
	v_cndmask_b32_e32 v41, v211, v41, vcc
	v_lshlrev_b32_e32 v65, 2, v41
	v_xor_b32_e32 v41, 8, v211
	v_cmp_lt_i32_e32 vcc, v41, v39
	v_readlane_b32 s12, v252, 44
	v_readlane_b32 s13, v252, 45
	v_cndmask_b32_e32 v41, v211, v41, vcc
	v_lshlrev_b32_e32 v66, 2, v41
	v_xor_b32_e32 v41, 4, v211
	v_cmp_lt_i32_e32 vcc, v41, v39
	v_readlane_b32 s18, v252, 50
	v_readlane_b32 s19, v252, 51
	v_cndmask_b32_e32 v41, v211, v41, vcc
	v_lshlrev_b32_e32 v67, 2, v41
	v_xor_b32_e32 v41, 2, v211
	v_cmp_lt_i32_e32 vcc, v41, v39
	s_mov_b64 s[14:15], 0x33601000
	v_add_u32_e32 v70, 0, v40
	v_cndmask_b32_e32 v41, v211, v41, vcc
	v_lshlrev_b32_e32 v68, 2, v41
	v_xor_b32_e32 v41, 1, v211
	v_cmp_lt_i32_e32 vcc, v41, v39
	v_or_b32_e32 v34, v34, v188
	s_mov_b64 s[18:19], 0
	v_cndmask_b32_e32 v39, v211, v41, vcc
	v_lshlrev_b32_e32 v69, 2, v39
	v_and_b32_e32 v39, 32, v38
	v_cmp_eq_u32_e64 s[4:5], 0, v39
	v_and_b32_e32 v39, 16, v38
	v_cmp_eq_u32_e64 s[6:7], 0, v39
	v_and_b32_e32 v39, 8, v38
	v_cmp_eq_u32_e64 s[8:9], 0, v39
	v_and_b32_e32 v39, 4, v38
	v_cmp_eq_u32_e64 s[10:11], 0, v39
	v_and_b32_e32 v39, 3, v38
	v_lshlrev_b32_e32 v38, 14, v38
	v_cmp_eq_u32_e64 s[12:13], 0, v39
	v_and_b32_e32 v38, 0xf0000, v38
	v_mov_b32_e32 v39, v189
	v_lshl_add_u64 v[38:39], v[32:33], 2, v[38:39]
	v_lshl_add_u64 v[38:39], v[38:39], 0, s[14:15]
	v_readlane_b32 s20, v252, 52
	v_readlane_b32 s21, v252, 53
	v_readlane_b32 s22, v252, 54
	v_readlane_b32 s23, v252, 55
	s_waitcnt vmcnt(3)
	v_mov_b64_e32 v[40:41], v[54:55]
	s_waitcnt vmcnt(2)
	v_mov_b64_e32 v[42:43], v[52:53]
	s_waitcnt vmcnt(1)
	v_mov_b64_e32 v[44:45], v[50:51]
	s_waitcnt vmcnt(0)
	v_mov_b64_e32 v[46:47], v[48:49]
	v_mov_b32_e32 v248, v32
	v_ashrrev_i32_e32 v249, 31, v32
	v_lshlrev_b64 v[246:247], 11, v[248:249]
	v_lshl_add_u64 v[246:247], v[36:37], 0, v[246:247]
	v_add_co_u32_e32 v246, vcc, 0x400000, v246
	s_nop 1
	v_addc_co_u32_e32 v247, vcc, 0, v247, vcc
	global_load_dwordx2 v[80:81], v[246:247], off nt
	global_load_dwordx2 v[82:83], v[246:247], off offset:512 nt
	global_load_dwordx2 v[84:85], v[246:247], off offset:1024 nt
	global_load_dwordx2 v[86:87], v[246:247], off offset:1536 nt
	v_add_co_u32_e32 v246, vcc, 0x400000, v246
	s_nop 1
	v_addc_co_u32_e32 v247, vcc, 0, v247, vcc
	global_load_dwordx2 v[88:89], v[246:247], off nt
	global_load_dwordx2 v[90:91], v[246:247], off offset:512 nt
	global_load_dwordx2 v[190:191], v[246:247], off offset:1024 nt
	global_load_dwordx2 v[192:193], v[246:247], off offset:1536 nt
	v_add_co_u32_e32 v246, vcc, 0x400000, v246
	s_nop 1
	v_addc_co_u32_e32 v247, vcc, 0, v247, vcc
	global_load_dwordx2 v[194:195], v[246:247], off nt
	global_load_dwordx2 v[196:197], v[246:247], off offset:512 nt
	global_load_dwordx2 v[198:199], v[246:247], off offset:1024 nt
	global_load_dwordx2 v[200:201], v[246:247], off offset:1536 nt
	v_add_co_u32_e32 v246, vcc, 0x400000, v246
	s_nop 1
	v_addc_co_u32_e32 v247, vcc, 0, v247, vcc
	global_load_dwordx2 v[202:203], v[246:247], off nt
	global_load_dwordx2 v[204:205], v[246:247], off offset:512 nt
	global_load_dwordx2 v[206:207], v[246:247], off offset:1024 nt
	global_load_dwordx2 v[208:209], v[246:247], off offset:1536 nt
	v_add_co_u32_e32 v246, vcc, 0x400000, v246
	s_nop 1
	v_addc_co_u32_e32 v247, vcc, 0, v247, vcc
	global_load_dwordx2 v[222:223], v[246:247], off nt
	global_load_dwordx2 v[224:225], v[246:247], off offset:512 nt
	global_load_dwordx2 v[226:227], v[246:247], off offset:1024 nt
	global_load_dwordx2 v[228:229], v[246:247], off offset:1536 nt
	v_add_co_u32_e32 v246, vcc, 0x400000, v246
	s_nop 1
	v_addc_co_u32_e32 v247, vcc, 0, v247, vcc
	global_load_dwordx2 v[230:231], v[246:247], off nt
	global_load_dwordx2 v[232:233], v[246:247], off offset:512 nt
	global_load_dwordx2 v[234:235], v[246:247], off offset:1024 nt
	global_load_dwordx2 v[236:237], v[246:247], off offset:1536 nt
	v_add_co_u32_e32 v246, vcc, 0x400000, v246
	s_nop 1
	v_addc_co_u32_e32 v247, vcc, 0, v247, vcc
	global_load_dwordx2 v[238:239], v[246:247], off nt
	global_load_dwordx2 v[240:241], v[246:247], off offset:512 nt
	global_load_dwordx2 v[242:243], v[246:247], off offset:1024 nt
	global_load_dwordx2 v[244:245], v[246:247], off offset:1536 nt
	s_mov_b32 s7, 1
	s_mov_b32 s6, 0
	s_branch .LBB0_314
